# P7 topk segment at s_setprio 1 (VALU-bound search over drifted convert waves) on top of the phase-8 v-side priority raise
# baseline (speedup 1.0000x reference)
; __device__ void topk_unit(const Params& p, unsigned char* smem, int unit) {
;   const int tid = threadIdx.x & 255, lane = tid & 63, wid = tid >> 6, l15 = lane & 15, q4 = lane >> 4;
;   const int h = unit & 7, tile = unit >> 3;
;   const int tok0 = tile * 64 + wid * 16;
;   unsigned char* ws = p.ws;
;   const bf16_t* qg = (const bf16_t*)(ws + OFF_Q);
;   const bf16_t* kb = (const bf16_t*)(ws + OFF_KEYSB);
;   unsigned* S = (unsigned*)(smem + wid * 16640);
;   float* tops = (float*)(smem + 4 * 16640 + wid * 256);
;   int* topi = (int*)(tops + 32);
;   unsigned* Ms = (unsigned*)(smem + 67584 + wid * 768);
; #pragma unroll
;   for (int k = 0; k < 2; ++k) {
;     f32x4 sc[8];
; #pragma unroll
;     for (int i = 0; i < 8; ++i) sc[i] = (f32x4){0, 0, 0, 0};
; #pragma unroll
;     for (int ks = 0; ks < 4; ++ks) {
;       bf16x8 qf = as_frag(*(const u32x4*)(qg + (size_t)(tok0 + l15) * DM + h * 256 + k * 128 + ks * 32 + q4 * 8));
; #pragma unroll
;       for (int nt = 0; nt < 8; ++nt) {
;         bf16x8 kf = as_frag(*(const u32x4*)(kb + (size_t)((h * 2 + k) * 128 + nt * 16 + l15) * 128 + ks * 32 + q4 * 8));
;         sc[nt] = mfma16(kf, qf, sc[nt]);
;       }
;     }
; #pragma unroll
;     for (int nt = 0; nt < 8; ++nt) {
;       const int n = nt * 16 + q4 * 4;
;       u32x4 kk;
; #pragma unroll
;       for (int r = 0; r < 4; ++r) kk[r] = (ord_key(sc[nt][r]) & ~127u) | (unsigned)(127 - (n + r));
;       *(u32x4*)(S + l15 * 260 + k * 128 + n) = kk;
;     }
;   }
;   const unsigned ct = cand_tab[lane];
;   const int ca = ct >> 4, cbb = ct & 15;
;   int* idxo = (int*)(ws + OFF_IDX);
;   float* go = (float*)(ws + OFF_G);
.LBB0_1082:
	s_setprio 1
	s_or_b64 exec, exec, s[10:11]
	s_and_saveexec_b64 s[22:23], s[0:1]
	s_cbranch_execz .LBB0_1130
	s_add_u32 s36, s34, 0x8000000
	s_addc_u32 s37, s35, 0
	s_getpc_b64 s[0:1]
	s_add_u32 s0, s0, _ZL8cand_tab@rel32@lo+4
	s_addc_u32 s1, s1, _ZL8cand_tab@rel32@hi+12
	global_load_ubyte v65, v138, s[0:1]
	s_waitcnt lgkmcnt(0)
	v_lshlrev_b64 v[2:3], v139, -1
	v_mbcnt_lo_u32_b32 v10, -1, 0
	v_mul_lo_u32 v5, s96, v1
	v_bfe_u32 v1, v139, 6, 2
	v_and_b32_e32 v96, 15, v139
	v_bfe_u32 v7, v139, 4, 2
	s_movk_i32 s3, 0x4100
	v_not_b32_e32 v64, v2
	v_mbcnt_hi_u32_b32 v2, -1, v10
	v_and_b32_e32 v62, 48, v139
	v_lshlrev_b32_e32 v12, 2, v138
	v_mad_u32_u24 v13, v1, s3, v166
	v_lshlrev_b32_e32 v6, 3, v7
	v_lshlrev_b32_e32 v98, 2, v7
	v_mul_u32_u24_e32 v7, 0x410, v96
	v_and_b32_e32 v102, 64, v2
	v_mov_b32_e32 v63, 0
	v_lshlrev_b32_e32 v97, 4, v1
	v_lshlrev_b32_e32 v14, 8, v1
	v_mul_u32_u24_e32 v15, 0x300, v1
	v_not_b32_e32 v1, v3
	v_add3_u32 v100, v13, v7, v62
	v_xor_b32_e32 v3, 32, v2
	v_add_u32_e32 v103, v13, v12
	v_add_u32_e32 v13, 64, v102
	s_mov_b64 s[0:1], 0x1d740000
	s_mov_b64 s[6:7], 0x1d740040
	s_mov_b64 s[8:9], 0x1d740080
	s_mov_b64 s[10:11], 0x1d7400c0
	v_lshl_add_u64 v[8:9], s[34:35], 0, v[62:63]
	v_xor_b32_e32 v7, 16, v2
	v_cmp_lt_i32_e32 vcc, v3, v13
	v_lshl_add_u64 v[66:67], v[8:9], 0, s[0:1]
	v_lshl_add_u64 v[68:69], v[8:9], 0, s[6:7]
	v_lshl_add_u64 v[70:71], v[8:9], 0, s[8:9]
	v_lshl_add_u64 v[72:73], v[8:9], 0, s[10:11]
	v_xor_b32_e32 v8, 8, v2
	v_cndmask_b32_e32 v3, v2, v3, vcc
	v_cmp_lt_i32_e32 vcc, v7, v13
	v_xor_b32_e32 v9, 4, v2
	s_mov_b32 s12, 0x10400
	v_cndmask_b32_e32 v7, v2, v7, vcc
	v_cmp_lt_i32_e32 vcc, v8, v13
	v_xor_b32_e32 v10, 2, v2
	v_add3_u32 v99, v166, v14, s12
	v_cndmask_b32_e32 v8, v2, v8, vcc
	v_cmp_lt_i32_e32 vcc, v9, v13
	v_xor_b32_e32 v14, 1, v2
	s_add_u32 s38, s34, 0xc000000
	v_cndmask_b32_e32 v9, v2, v9, vcc
	v_cmp_lt_i32_e32 vcc, v10, v13
	v_lshlrev_b32_e32 v106, 2, v3
	s_addc_u32 s39, s35, 0
	v_cndmask_b32_e32 v10, v2, v10, vcc
	v_cmp_lt_i32_e32 vcc, v14, v13
	s_add_u32 s40, s34, 0xc800000
	s_mov_b32 s13, 0x10800
	v_cndmask_b32_e32 v2, v2, v14, vcc
	v_lshlrev_b32_e32 v111, 2, v2
	s_addc_u32 s41, s35, 0
	v_lshlrev_b32_e32 v74, 3, v5
	s_lshl_b32 s49, s96, 4
	s_lshl_b32 s0, s2, 1
	v_and_b32_e32 v11, 31, v139
	v_lshlrev_b32_e32 v4, 5, v138
	v_add3_u32 v101, v166, v15, s13
	v_lshlrev_b32_e32 v62, 4, v138
	v_ashrrev_i32_e32 v75, 31, v74
	s_mov_b32 s48, 0
	v_cmp_gt_u32_e64 s[14:15], 32, v138
	v_cmp_gt_u32_e64 s[4:5], 50, v138
	v_add_u32_e32 v104, v101, v12
	v_lshl_add_u32 v105, v11, 2, v101
	v_lshlrev_b32_e32 v107, 2, v7
	v_lshlrev_b32_e32 v108, 2, v8
	v_lshlrev_b32_e32 v109, 2, v9
	v_lshlrev_b32_e32 v110, 2, v10
	v_cmp_eq_u32_e64 s[6:7], 0, v138
	v_add_u16_e32 v115, s0, v165
	s_waitcnt vmcnt(0)
	v_lshrrev_b32_e32 v3, 2, v65
	v_and_b32_e32 v2, 15, v65
	v_and_b32_e32 v3, 60, v3
	v_lshl_add_u32 v112, v2, 2, v99
	v_add_u32_e32 v113, v99, v3
	v_lshlrev_b32_e32 v2, 7, v138
	v_mov_b32_e32 v3, v63
	v_lshl_add_u64 v[76:77], s[18:19], 0, v[2:3]
	v_lshlrev_b32_e32 v2, 3, v165
	v_lshl_add_u32 v114, s2, 4, v2
	s_add_u32 s18, s34, 0x1dc90000
	v_lshlrev_b32_e32 v2, 11, v164
	s_addc_u32 s19, s35, 0
	v_lshl_add_u32 v78, s2, 3, v164
	s_lshl_b32 s50, s96, 3
	v_lshlrev_b64 v[80:81], 2, v[74:75]
	v_lshl_add_u64 v[82:83], s[34:35], 0, v[62:63]
	v_lshlrev_b64 v[84:85], 10, v[74:75]
	v_lshl_add_u32 v75, s2, 14, v2
	s_lshl_b32 s51, s96, 14
	v_lshlrev_b32_e32 v116, 14, v5
	s_mov_b64 s[42:43], 0
	s_movk_i32 s52, 0xffc0
	v_lshlrev_b32_e32 v86, 1, v6
	v_mov_b32_e32 v87, v63
	v_lshlrev_b32_e32 v117, 8, v96
	s_movk_i32 s53, 0x4000
	v_bfrev_b32_e32 v118, 1
	s_movk_i32 s54, 0xff80
	s_movk_i32 s55, 0x7f
	s_movk_i32 s56, 0x6f
	s_movk_i32 s57, 0x5f
	s_movk_i32 s58, 0x4f
	s_mov_b32 s59, 0x8000
	s_movk_i32 s60, 0xff00
	s_movk_i32 s61, 0xff
	s_mov_b64 s[44:45], 0x80
	s_movk_i32 s62, 0x3fff
	v_lshlrev_b32_e32 v88, 2, v4
	s_mov_b32 s63, 0xf800000
	v_mov_b32_e32 v119, 0x260
	s_mov_b32 s64, 0xc0e00000
	s_movk_i32 s65, 0x80
	s_movk_i32 s66, 0x7fff
	s_movk_i32 s67, 0x7ff
	v_mov_b32_e32 v120, 0x40e00000
	v_mov_b32_e32 v249, -1
	s_branch .LBB0_1085

; #define PHASE_SYNC(n) if (p.coop && PHASE_ON(n) && (n) < p.phase_hi) { if (p.coop == 2) grid.sync(); else xcd_barrier(xb); }
; __global__ void __launch_bounds__(NTHR, 2) fwd_kernel(Params p) {
;     ...
;     for (int u = u_first; u < 2048; u += u_step, ++kk) {
;       topk_unit(p, hsm, u);
;       convert_uv(p, kk, nk);
;     }
;   }
;   PHASE_SYNC(7)
.LBB0_1130:
	s_setprio 0
	s_or_b64 exec, exec, s[22:23]
	v_readlane_b32 s56, v250, 6
	v_readlane_b32 s57, v250, 7
	v_readlane_b32 s58, v250, 8
	v_readlane_b32 s59, v250, 9
